# topbar + the now-unread release generation bumps (per-XCC and cross-XCC) removed from the leaders' barrier exit path
# speedup vs baseline: 1.0106x; 1.0106x over previous
.LBB0_144:
	s_or_b64 exec, exec, s[22:23]
	v_cvt_f32_u32_e32 v4, v1
	s_waitcnt vmcnt(0)
	v_readfirstlane_b32 s3, v3
	s_mov_b64 s[22:23], 0
	v_rcp_iflag_f32_e32 v4, v4
	v_add_u32_e32 v2, s3, v2
	v_add_u32_e32 v5, 1, v2
	v_mul_f32_e32 v3, 0x4f7ffffe, v4
	v_cvt_u32_f32_e32 v3, v3
	v_sub_u32_e32 v4, 0, v1
	v_mul_lo_u32 v4, v4, v3
	v_mul_hi_u32 v4, v3, v4
	v_add_u32_e32 v3, v3, v4
	v_mul_hi_u32 v3, v2, v3
	v_mul_lo_u32 v4, v3, v1
	v_sub_u32_e32 v2, v2, v4
	v_add_u32_e32 v6, 1, v3
	v_cmp_ge_u32_e32 vcc, v2, v1
	v_sub_u32_e32 v4, v2, v1
	s_nop 0
	v_cndmask_b32_e32 v3, v3, v6, vcc
	v_cndmask_b32_e32 v2, v2, v4, vcc
	v_add_u32_e32 v4, 1, v3
	v_cmp_ge_u32_e32 vcc, v2, v1
	s_nop 1
	v_cndmask_b32_e32 v4, v3, v4, vcc
	v_mul_lo_u32 v2, v1, v4
	v_add_u32_e32 v1, v2, v1
	v_cmp_ne_u32_e32 vcc, v5, v1
	v_mov_b32_e32 v4, v1
	v_mov_b64_e32 v[2:3], s[92:93]
	s_and_saveexec_b64 s[20:21], vcc
	s_cbranch_execz .LBB0_156
	v_mov_b32_e32 v1, 0
	global_load_dword v2, v1, s[92:93] offset:-256 sc1
	s_mov_b64 s[24:25], 0
	s_waitcnt vmcnt(0)
	v_cmp_gt_u32_e32 vcc, v4, v2
	s_and_saveexec_b64 s[22:23], vcc
	s_cbranch_execz .LBB0_155
	s_mov_b32 s3, 1
	s_branch .LBB0_148

.LBB0_158:
	s_or_b64 exec, exec, s[20:21]
	s_mov_b64 s[20:21], exec
	v_mbcnt_lo_u32_b32 v1, s20, 0
	v_mbcnt_hi_u32_b32 v1, s21, v1
	v_cmp_eq_u32_e32 vcc, 0, v1
	s_waitcnt vmcnt(0)
	buffer_inv sc1
	s_and_saveexec_b64 s[22:23], vcc
	s_cbranch_execz .LBB0_160
	s_bcnt1_i32_b64 s3, s[20:21]
	v_mov_b32_e32 v1, 0
	v_mov_b32_e32 v2, s3
.LBB0_160:
	s_or_b64 exec, exec, s[22:23]
	s_waitcnt vmcnt(0)

.LBB0_361:
	s_or_b64 exec, exec, s[22:23]
	v_cvt_f32_u32_e32 v4, v1
	s_waitcnt vmcnt(0)
	v_readfirstlane_b32 s4, v3
	s_mov_b64 s[22:23], 0
	v_rcp_iflag_f32_e32 v4, v4
	v_add_u32_e32 v2, s4, v2
	v_add_u32_e32 v5, 1, v2
	v_mul_f32_e32 v3, 0x4f7ffffe, v4
	v_cvt_u32_f32_e32 v3, v3
	v_sub_u32_e32 v4, 0, v1
	v_mul_lo_u32 v4, v4, v3
	v_mul_hi_u32 v4, v3, v4
	v_add_u32_e32 v3, v3, v4
	v_mul_hi_u32 v3, v2, v3
	v_mul_lo_u32 v4, v3, v1
	v_sub_u32_e32 v2, v2, v4
	v_add_u32_e32 v6, 1, v3
	v_cmp_ge_u32_e32 vcc, v2, v1
	v_sub_u32_e32 v4, v2, v1
	s_nop 0
	v_cndmask_b32_e32 v3, v3, v6, vcc
	v_cndmask_b32_e32 v2, v2, v4, vcc
	v_add_u32_e32 v4, 1, v3
	v_cmp_ge_u32_e32 vcc, v2, v1
	s_nop 1
	v_cndmask_b32_e32 v4, v3, v4, vcc
	v_mul_lo_u32 v2, v1, v4
	v_add_u32_e32 v1, v2, v1
	v_cmp_ne_u32_e32 vcc, v5, v1
	v_mov_b32_e32 v4, v1
	v_mov_b64_e32 v[2:3], s[92:93]
	s_and_saveexec_b64 s[20:21], vcc
	s_cbranch_execz .LBB0_373
	v_mov_b32_e32 v1, 0
	global_load_dword v2, v1, s[92:93] offset:-256 sc1
	s_mov_b64 s[24:25], 0
	s_waitcnt vmcnt(0)
	v_cmp_gt_u32_e32 vcc, v4, v2
	s_and_saveexec_b64 s[22:23], vcc
	s_cbranch_execz .LBB0_372
	s_mov_b32 s4, 1
	s_branch .LBB0_365

.LBB0_375:
	s_or_b64 exec, exec, s[20:21]
	s_mov_b64 s[20:21], exec
	v_mbcnt_lo_u32_b32 v1, s20, 0
	v_mbcnt_hi_u32_b32 v1, s21, v1
	v_cmp_eq_u32_e32 vcc, 0, v1
	s_waitcnt vmcnt(0)
	buffer_inv sc1
	s_and_saveexec_b64 s[22:23], vcc
	s_cbranch_execz .LBB0_377
	s_bcnt1_i32_b64 s4, s[20:21]
	v_mov_b32_e32 v1, 0
	v_mov_b32_e32 v2, s4
.LBB0_377:
	s_or_b64 exec, exec, s[22:23]
	s_waitcnt vmcnt(0)

.LBB0_512:
	s_or_b64 exec, exec, s[20:21]
	s_mov_b64 s[20:21], exec
	v_mbcnt_lo_u32_b32 v1, s20, 0
	v_mbcnt_hi_u32_b32 v1, s21, v1
	v_cmp_eq_u32_e32 vcc, 0, v1
	s_waitcnt vmcnt(0)
	buffer_inv sc1
	s_and_saveexec_b64 s[22:23], vcc
	s_cbranch_execz .LBB0_514
	s_bcnt1_i32_b64 s4, s[20:21]
	v_mov_b32_e32 v1, 0
	v_mov_b32_e32 v2, s4
.LBB0_514:
	s_or_b64 exec, exec, s[22:23]
	s_waitcnt vmcnt(0)

.LBB0_631:
	s_or_b64 exec, exec, s[22:23]
	s_waitcnt vmcnt(0)
	v_readfirstlane_b32 s4, v4
	v_cvt_f32_u32_e32 v4, v2
	v_sub_u32_e32 v5, 0, v2
	v_add_u32_e32 v3, s4, v3
	s_mov_b64 s[22:23], 0
	v_rcp_iflag_f32_e32 v4, v4
	s_nop 0
	v_mul_f32_e32 v4, 0x4f7ffffe, v4
	v_cvt_u32_f32_e32 v4, v4
	v_mul_lo_u32 v5, v5, v4
	v_mul_hi_u32 v5, v4, v5
	v_add_u32_e32 v4, v4, v5
	v_mul_hi_u32 v4, v3, v4
	v_mul_lo_u32 v5, v4, v2
	v_sub_u32_e32 v5, v3, v5
	v_cmp_ge_u32_e32 vcc, v5, v2
	v_add_u32_e32 v6, 1, v4
	v_add_u32_e32 v3, 1, v3
	v_cndmask_b32_e32 v4, v4, v6, vcc
	v_sub_u32_e32 v6, v5, v2
	v_cndmask_b32_e32 v5, v5, v6, vcc
	v_cmp_ge_u32_e32 vcc, v5, v2
	v_add_u32_e32 v5, 1, v4
	s_nop 0
	v_cndmask_b32_e32 v4, v4, v5, vcc
	v_mul_lo_u32 v5, v2, v4
	v_add_u32_e32 v2, v5, v2
	v_cmp_ne_u32_e32 vcc, v3, v2
	v_mov_b32_e32 v4, v2
	v_mov_b64_e32 v[2:3], s[92:93]
	s_and_saveexec_b64 s[20:21], vcc
	s_cbranch_execz .LBB0_643
	v_mov_b32_e32 v2, 0
	global_load_dword v3, v2, s[92:93] offset:-256 sc1
	s_mov_b64 s[24:25], 0
	s_waitcnt vmcnt(0)
	v_cmp_gt_u32_e32 vcc, v4, v3
	s_and_saveexec_b64 s[22:23], vcc
	s_cbranch_execz .LBB0_642
	s_mov_b32 s4, 1
	s_branch .LBB0_635

.LBB0_645:
	s_or_b64 exec, exec, s[20:21]
	s_mov_b64 s[20:21], exec
	v_mbcnt_lo_u32_b32 v2, s20, 0
	v_mbcnt_hi_u32_b32 v2, s21, v2
	v_cmp_eq_u32_e32 vcc, 0, v2
	s_waitcnt vmcnt(0)
	buffer_inv sc1
	s_and_saveexec_b64 s[22:23], vcc
	s_cbranch_execz .LBB0_647
	s_bcnt1_i32_b64 s4, s[20:21]
	v_mov_b32_e32 v2, 0
	v_mov_b32_e32 v3, s4
.LBB0_647:
	s_or_b64 exec, exec, s[22:23]
	s_waitcnt vmcnt(0)

.LBB0_720:
	s_or_b64 exec, exec, s[20:21]
	s_mov_b64 s[20:21], exec
	v_mbcnt_lo_u32_b32 v2, s20, 0
	v_mbcnt_hi_u32_b32 v2, s21, v2
	v_cmp_eq_u32_e32 vcc, 0, v2
	s_waitcnt vmcnt(0)
	buffer_inv sc1
	s_and_saveexec_b64 s[22:23], vcc
	s_cbranch_execz .LBB0_722
	s_bcnt1_i32_b64 s4, s[20:21]
	v_mov_b32_e32 v2, 0
	v_mov_b32_e32 v3, s4
.LBB0_722:
	s_or_b64 exec, exec, s[22:23]
	s_waitcnt vmcnt(0)

.LBB0_1576:
	s_or_b64 exec, exec, s[20:21]
	s_waitcnt vmcnt(0)
	v_readfirstlane_b32 s4, v4
	v_cvt_f32_u32_e32 v4, v2
	v_sub_u32_e32 v5, 0, v2
	v_add_u32_e32 v3, s4, v3
	s_mov_b64 s[20:21], 0
	v_rcp_iflag_f32_e32 v4, v4
	s_nop 0
	v_mul_f32_e32 v4, 0x4f7ffffe, v4
	v_cvt_u32_f32_e32 v4, v4
	v_mul_lo_u32 v5, v5, v4
	v_mul_hi_u32 v5, v4, v5
	v_add_u32_e32 v4, v4, v5
	v_mul_hi_u32 v4, v3, v4
	v_mul_lo_u32 v5, v4, v2
	v_sub_u32_e32 v5, v3, v5
	v_cmp_ge_u32_e32 vcc, v5, v2
	v_add_u32_e32 v6, 1, v4
	v_add_u32_e32 v3, 1, v3
	v_cndmask_b32_e32 v4, v4, v6, vcc
	v_sub_u32_e32 v6, v5, v2
	v_cndmask_b32_e32 v5, v5, v6, vcc
	v_cmp_ge_u32_e32 vcc, v5, v2
	v_add_u32_e32 v5, 1, v4
	s_nop 0
	v_cndmask_b32_e32 v4, v4, v5, vcc
	v_mul_lo_u32 v5, v2, v4
	v_add_u32_e32 v2, v5, v2
	v_cmp_ne_u32_e32 vcc, v3, v2
	v_mov_b32_e32 v4, v2
	v_mov_b64_e32 v[2:3], s[92:93]
	s_and_saveexec_b64 s[18:19], vcc
	s_cbranch_execz .LBB0_1588
	v_mov_b32_e32 v2, 0
	global_load_dword v3, v2, s[92:93] offset:-256 sc1
	s_mov_b64 s[22:23], 0
	s_waitcnt vmcnt(0)
	v_cmp_gt_u32_e32 vcc, v4, v3
	s_and_saveexec_b64 s[20:21], vcc
	s_cbranch_execz .LBB0_1587
	s_mov_b32 s4, 1
	s_branch .LBB0_1580

.LBB0_1590:
	s_or_b64 exec, exec, s[18:19]
	s_mov_b64 s[18:19], exec
	v_mbcnt_lo_u32_b32 v2, s18, 0
	v_mbcnt_hi_u32_b32 v2, s19, v2
	v_cmp_eq_u32_e32 vcc, 0, v2
	s_waitcnt vmcnt(0)
	buffer_inv sc1
	s_and_saveexec_b64 s[20:21], vcc
	s_cbranch_execz .LBB0_1592
	s_bcnt1_i32_b64 s4, s[18:19]
	v_mov_b32_e32 v2, 0
	v_mov_b32_e32 v3, s4
.LBB0_1592:
	s_or_b64 exec, exec, s[20:21]
	s_waitcnt vmcnt(0)

.LBB0_1663:
	s_or_b64 exec, exec, s[6:7]
	v_cvt_f32_u32_e32 v4, v1
	s_waitcnt vmcnt(0)
	v_readfirstlane_b32 s4, v3
	s_mov_b64 s[6:7], 0
	v_rcp_iflag_f32_e32 v4, v4
	v_add_u32_e32 v2, s4, v2
	v_add_u32_e32 v5, 1, v2
	v_mul_f32_e32 v3, 0x4f7ffffe, v4
	v_cvt_u32_f32_e32 v3, v3
	v_sub_u32_e32 v4, 0, v1
	v_mul_lo_u32 v4, v4, v3
	v_mul_hi_u32 v4, v3, v4
	v_add_u32_e32 v3, v3, v4
	v_mul_hi_u32 v3, v2, v3
	v_mul_lo_u32 v4, v3, v1
	v_sub_u32_e32 v2, v2, v4
	v_add_u32_e32 v6, 1, v3
	v_cmp_ge_u32_e32 vcc, v2, v1
	v_sub_u32_e32 v4, v2, v1
	s_nop 0
	v_cndmask_b32_e32 v3, v3, v6, vcc
	v_cndmask_b32_e32 v2, v2, v4, vcc
	v_add_u32_e32 v4, 1, v3
	v_cmp_ge_u32_e32 vcc, v2, v1
	s_nop 1
	v_cndmask_b32_e32 v4, v3, v4, vcc
	v_mul_lo_u32 v2, v1, v4
	v_add_u32_e32 v1, v2, v1
	v_cmp_ne_u32_e32 vcc, v5, v1
	v_mov_b32_e32 v4, v1
	v_mov_b64_e32 v[2:3], s[92:93]
	s_and_saveexec_b64 s[4:5], vcc
	s_cbranch_execz .LBB0_1675
	v_mov_b32_e32 v1, 0
	global_load_dword v2, v1, s[92:93] offset:-256 sc1
	s_mov_b64 s[8:9], 0
	s_waitcnt vmcnt(0)
	v_cmp_gt_u32_e32 vcc, v4, v2
	s_and_saveexec_b64 s[6:7], vcc
	s_cbranch_execz .LBB0_1674
	s_mov_b32 s18, 1
	s_branch .LBB0_1667

.LBB0_1677:
	s_or_b64 exec, exec, s[4:5]
	s_mov_b64 s[4:5], exec
	v_mbcnt_lo_u32_b32 v1, s4, 0
	v_mbcnt_hi_u32_b32 v1, s5, v1
	v_cmp_eq_u32_e32 vcc, 0, v1
	s_waitcnt vmcnt(0)
	buffer_inv sc1
	s_and_saveexec_b64 s[6:7], vcc
	s_cbranch_execz .LBB0_1679
	s_bcnt1_i32_b64 s4, s[4:5]
	v_mov_b32_e32 v1, 0
	v_mov_b32_e32 v2, s4
.LBB0_1679:
	s_or_b64 exec, exec, s[6:7]
	s_waitcnt vmcnt(0)
